# B1 cross-attention item: score MFMAs with K fragment reads six ahead through rotating buffers, in-place accumulation
# baseline (speedup 1.0000x reference)
.LBB0_330:
	s_or_b64 exec, exec, s[0:1]
	s_movk_i32 s0, 0x407
	v_cmp_lt_i32_e32 vcc, s0, v206
	s_and_saveexec_b64 s[0:1], vcc
	s_xor_b64 s[96:97], exec, s[0:1]
	s_cbranch_execz .LBB0_405
	s_movk_i32 s0, 0x447
	v_cmp_lt_u32_e32 vcc, s0, v206
	s_and_saveexec_b64 s[0:1], vcc
	s_xor_b64 s[56:57], exec, s[0:1]
	s_cbranch_execz .LBB0_364
	s_movk_i32 s0, 0x64b
	v_cmp_lt_u32_e32 vcc, s0, v206
	s_and_saveexec_b64 s[0:1], vcc
	s_xor_b64 s[0:1], exec, s[0:1]
	s_cbranch_execz .LBB0_334
	v_add_u32_e32 v48, 0xfffff9b4, v206
	v_lshrrev_b32_e32 v50, 6, v48
	v_bfe_u32 v51, v48, 4, 2
	v_lshl_add_u32 v0, v50, 2, s37
	v_or_b32_e32 v0, v0, v51
	v_ashrrev_i32_e32 v1, 31, v0
	v_readlane_b32 s20, v214, 37
	v_mov_b32_e32 v49, v133
	v_lshlrev_b64 v[0:1], 15, v[0:1]
	v_readlane_b32 s21, v214, 38
	s_nop 0
	v_lshlrev_b32_e32 v4, 4, v49
	v_lshl_add_u64 v[2:3], s[20:21], 0, v[0:1]
	v_readlane_b32 s20, v214, 39
	v_readlane_b32 s21, v214, 40
	v_and_b32_e32 v64, 0x70, v4
	v_lshl_add_u64 v[24:25], v[2:3], 0, v[64:65]
	v_lshl_add_u64 v[0:1], s[20:21], 0, v[0:1]
	v_add_u32_e32 v32, 0, v64
	v_and_b32_e32 v64, 0x1f0, v4
	v_ashrrev_i32_e32 v33, 3, v49
	v_lshl_add_u64 v[28:29], v[0:1], 0, v[64:65]
	v_lshlrev_b32_e32 v0, 6, v33
	v_ashrrev_i32_e32 v41, 5, v49
	v_add_u32_e32 v12, 0x200, v49
	v_ashrrev_i32_e32 v1, 31, v0
	v_lshlrev_b32_e32 v4, 8, v41
	v_ashrrev_i32_e32 v36, 3, v12
	v_lshl_add_u64 v[0:1], v[0:1], 1, v[24:25]
	v_ashrrev_i32_e32 v5, 31, v4
	v_lshlrev_b32_e32 v8, 6, v36
	v_ashrrev_i32_e32 v44, 5, v12
	v_add_u32_e32 v20, 0x400, v49
	s_barrier
	global_load_dwordx4 v[0:3], v[0:1], off
	v_lshl_add_u64 v[4:5], v[4:5], 1, v[28:29]
	v_ashrrev_i32_e32 v9, 31, v8
	v_lshlrev_b32_e32 v12, 8, v44
	v_ashrrev_i32_e32 v38, 3, v20
	global_load_dwordx4 v[4:7], v[4:5], off
	v_lshl_add_u64 v[8:9], v[8:9], 1, v[24:25]
	v_ashrrev_i32_e32 v13, 31, v12
	v_lshlrev_b32_e32 v16, 6, v38
	v_ashrrev_i32_e32 v46, 5, v20
	v_add_u32_e32 v30, 0x600, v49
	global_load_dwordx4 v[8:11], v[8:9], off
	v_lshl_add_u64 v[12:13], v[12:13], 1, v[28:29]
	v_ashrrev_i32_e32 v17, 31, v16
	v_lshlrev_b32_e32 v20, 8, v46
	v_ashrrev_i32_e32 v40, 3, v30
	global_load_dwordx4 v[12:15], v[12:13], off
	v_lshl_add_u64 v[16:17], v[16:17], 1, v[24:25]
	v_ashrrev_i32_e32 v21, 31, v20
	v_lshlrev_b32_e32 v26, 6, v40
	v_ashrrev_i32_e32 v52, 5, v30
	global_load_dwordx4 v[16:19], v[16:17], off
	v_lshl_add_u64 v[20:21], v[20:21], 1, v[28:29]
	v_ashrrev_i32_e32 v27, 31, v26
	v_lshlrev_b32_e32 v30, 8, v52
	global_load_dwordx4 v[20:23], v[20:21], off
	v_lshl_add_u64 v[24:25], v[26:27], 1, v[24:25]
	v_ashrrev_i32_e32 v31, 31, v30
	global_load_dwordx4 v[24:27], v[24:25], off
	v_lshl_add_u64 v[28:29], v[30:31], 1, v[28:29]
	global_load_dwordx4 v[28:31], v[28:29], off
	s_movk_i32 s22, 0x90
	v_mad_u64_u32 v[34:35], s[20:21], v33, s22, v[32:33]
	v_mad_u64_u32 v[36:37], s[20:21], v36, s22, v[32:33]
	v_mad_u64_u32 v[38:39], s[20:21], v38, s22, v[32:33]
	v_mad_u64_u32 v[32:33], s[20:21], v40, s22, v[32:33]
	v_add_u32_e32 v40, 0, v64
	v_mad_u64_u32 v[42:43], s[20:21], v41, s26, v[40:41]
	v_mad_u64_u32 v[44:45], s[20:21], v44, s26, v[40:41]
	v_mad_u64_u32 v[46:47], s[20:21], v46, s26, v[40:41]
	v_mad_u64_u32 v[40:41], s[20:21], v52, s26, v[40:41]
	v_and_b32_e32 v74, 15, v49
	v_readlane_b32 s20, v214, 12
	v_readlane_b32 s21, v214, 13
	v_bfe_u32 v71, v49, 4, 2
	v_lshlrev_b32_e32 v64, 7, v51
	s_movk_i32 s2, 0x1000
	s_movk_i32 s79, 0x90
	s_waitcnt vmcnt(7)
	ds_write_b128 v34, v[0:3]
	s_waitcnt vmcnt(6)
	ds_write_b128 v42, v[4:7] offset:36864
	s_waitcnt vmcnt(5)
	ds_write_b128 v36, v[8:11]
	s_waitcnt vmcnt(4)
	ds_write_b128 v44, v[12:15] offset:36864
	s_waitcnt vmcnt(3)
	ds_write_b128 v38, v[16:19]
	s_waitcnt vmcnt(2)
	ds_write_b128 v46, v[20:23] offset:36864
	s_waitcnt vmcnt(1)
	ds_write_b128 v32, v[24:27]
	s_waitcnt vmcnt(0)
	ds_write_b128 v40, v[28:31] offset:36864
	v_lshlrev_b32_e32 v1, 7, v48
	v_lshlrev_b32_e32 v0, 11, v50
	v_and_b32_e32 v1, 0x780, v1
	v_ashrrev_i32_e32 v2, 2, v49
	v_and_b32_e32 v2, -16, v2
	v_or3_b32 v0, v0, v1, v74
	v_add_u32_e32 v70, v0, v2
	v_mov_b64_e32 v[0:1], s[20:21]
	v_mad_i64_i32 v[0:1], s[20:21], v70, s83, v[0:1]
	v_lshlrev_b32_e32 v4, 4, v71
	v_mov_b32_e32 v5, v65
	v_lshl_add_u64 v[72:73], v[0:1], 0, v[64:65]
	v_lshl_add_u64 v[36:37], v[72:73], 0, v[4:5]
	v_add_co_u32_e32 v0, vcc, s2, v36
	s_waitcnt lgkmcnt(0)
	s_nop 0
	v_addc_co_u32_e32 v1, vcc, 0, v37, vcc
	s_barrier
	global_load_dwordx4 v[0:3], v[0:1], off offset:1280
	s_mov_b64 s[20:21], 0x1500
	v_lshl_add_u64 v[36:37], v[36:37], 0, s[20:21]
	global_load_dwordx4 v[66:69], v[36:37], off offset:64
	v_add_u32_e32 v75, 0, v4
	v_mad_u32_u24 v104, v74, s22, v75
	s_mov_b32 s20, 0xf149f2ca
	s_movk_i32 s73, 0x1000
	ds_read_b128 v[108:111], v104 offset:0
	ds_read_b128 v[112:115], v104 offset:2304
	ds_read_b128 v[116:119], v104 offset:64
	ds_read_b128 v[120:123], v104 offset:2368
	ds_read_b128 v[124:127], v104 offset:4608
	ds_read_b128 v[128:131], v104 offset:6912
	s_waitcnt vmcnt(1) lgkmcnt(5)
	v_mfma_f32_16x16x32_bf16 v[60:63], v[108:111], v[0:3], 0
	ds_read_b128 v[108:111], v104 offset:4672
	s_waitcnt lgkmcnt(5)
	v_mfma_f32_16x16x32_bf16 v[56:59], v[112:115], v[0:3], 0
	ds_read_b128 v[112:115], v104 offset:6976
	s_waitcnt vmcnt(0) lgkmcnt(5)
	v_mfma_f32_16x16x32_bf16 v[60:63], v[116:119], v[66:69], v[60:63]
	ds_read_b128 v[116:119], v104 offset:9216
	s_waitcnt lgkmcnt(5)
	v_mfma_f32_16x16x32_bf16 v[56:59], v[120:123], v[66:69], v[56:59]
	ds_read_b128 v[120:123], v104 offset:11520
	s_waitcnt lgkmcnt(5)
	v_mfma_f32_16x16x32_bf16 v[52:55], v[124:127], v[0:3], 0
	ds_read_b128 v[124:127], v104 offset:9280
	s_waitcnt lgkmcnt(5)
	v_mfma_f32_16x16x32_bf16 v[48:51], v[128:131], v[0:3], 0
	ds_read_b128 v[128:131], v104 offset:11584
	s_waitcnt lgkmcnt(5)
	v_mfma_f32_16x16x32_bf16 v[52:55], v[108:111], v[66:69], v[52:55]
	ds_read_b128 v[108:111], v104 offset:13824
	s_waitcnt lgkmcnt(5)
	v_mfma_f32_16x16x32_bf16 v[48:51], v[112:115], v[66:69], v[48:51]
	ds_read_b128 v[112:115], v104 offset:16128
	s_waitcnt lgkmcnt(5)
	v_mfma_f32_16x16x32_bf16 v[44:47], v[116:119], v[0:3], 0
	ds_read_b128 v[116:119], v104 offset:13888
	s_waitcnt lgkmcnt(5)
	v_mfma_f32_16x16x32_bf16 v[40:43], v[120:123], v[0:3], 0
	ds_read_b128 v[120:123], v104 offset:16192
	s_waitcnt lgkmcnt(5)
	v_mfma_f32_16x16x32_bf16 v[44:47], v[124:127], v[66:69], v[44:47]
	ds_read_b128 v[124:127], v104 offset:18432
	s_waitcnt lgkmcnt(5)
	v_mfma_f32_16x16x32_bf16 v[40:43], v[128:131], v[66:69], v[40:43]
	ds_read_b128 v[128:131], v104 offset:20736
	s_waitcnt lgkmcnt(5)
	v_mfma_f32_16x16x32_bf16 v[36:39], v[108:111], v[0:3], 0
	ds_read_b128 v[108:111], v104 offset:18496
	s_waitcnt lgkmcnt(5)
	v_mfma_f32_16x16x32_bf16 v[32:35], v[112:115], v[0:3], 0
	ds_read_b128 v[112:115], v104 offset:20800
	s_waitcnt lgkmcnt(5)
	v_mfma_f32_16x16x32_bf16 v[36:39], v[116:119], v[66:69], v[36:39]
	ds_read_b128 v[116:119], v104 offset:23040
	s_waitcnt lgkmcnt(5)
	v_mfma_f32_16x16x32_bf16 v[32:35], v[120:123], v[66:69], v[32:35]
	ds_read_b128 v[120:123], v104 offset:25344
	s_waitcnt lgkmcnt(5)
	v_mfma_f32_16x16x32_bf16 v[28:31], v[124:127], v[0:3], 0
	ds_read_b128 v[124:127], v104 offset:23104
	s_waitcnt lgkmcnt(5)
	v_mfma_f32_16x16x32_bf16 v[24:27], v[128:131], v[0:3], 0
	ds_read_b128 v[128:131], v104 offset:25408
	s_waitcnt lgkmcnt(5)
	v_mfma_f32_16x16x32_bf16 v[28:31], v[108:111], v[66:69], v[28:31]
	ds_read_b128 v[108:111], v104 offset:27648
	s_waitcnt lgkmcnt(5)
	v_mfma_f32_16x16x32_bf16 v[24:27], v[112:115], v[66:69], v[24:27]
	ds_read_b128 v[112:115], v104 offset:29952
	s_waitcnt lgkmcnt(5)
	v_mfma_f32_16x16x32_bf16 v[20:23], v[116:119], v[0:3], 0
	ds_read_b128 v[116:119], v104 offset:27712
	s_waitcnt lgkmcnt(5)
	v_mfma_f32_16x16x32_bf16 v[16:19], v[120:123], v[0:3], 0
	ds_read_b128 v[120:123], v104 offset:30016
	s_waitcnt lgkmcnt(5)
	v_mfma_f32_16x16x32_bf16 v[20:23], v[124:127], v[66:69], v[20:23]
	ds_read_b128 v[124:127], v104 offset:32256
	s_waitcnt lgkmcnt(5)
	v_mfma_f32_16x16x32_bf16 v[16:19], v[128:131], v[66:69], v[16:19]
	ds_read_b128 v[128:131], v104 offset:34560
	s_waitcnt lgkmcnt(5)
	v_mfma_f32_16x16x32_bf16 v[12:15], v[108:111], v[0:3], 0
	ds_read_b128 v[108:111], v104 offset:32320
	s_waitcnt lgkmcnt(5)
	v_mfma_f32_16x16x32_bf16 v[8:11], v[112:115], v[0:3], 0
	ds_read_b128 v[112:115], v104 offset:34624
	s_waitcnt lgkmcnt(5)
	v_mfma_f32_16x16x32_bf16 v[12:15], v[116:119], v[66:69], v[12:15]
	s_waitcnt lgkmcnt(4)
	v_mfma_f32_16x16x32_bf16 v[8:11], v[120:123], v[66:69], v[8:11]
	s_waitcnt lgkmcnt(3)
	v_mfma_f32_16x16x32_bf16 v[4:7], v[124:127], v[0:3], 0
	s_waitcnt lgkmcnt(2)
	v_mfma_f32_16x16x32_bf16 v[0:3], v[128:131], v[0:3], 0
	s_waitcnt lgkmcnt(1)
	v_mfma_f32_16x16x32_bf16 v[4:7], v[108:111], v[66:69], v[4:7]
	s_waitcnt lgkmcnt(0)
	v_mfma_f32_16x16x32_bf16 v[0:3], v[112:115], v[66:69], v[0:3]
	s_nop 7
	v_max_f32_e32 v66, v63, v63
	v_max_f32_e32 v67, v62, v62
	v_max_f32_e32 v66, v67, v66
	v_max_f32_e32 v67, v59, v59
	v_max_f32_e32 v68, v58, v58
	v_max_f32_e32 v67, v68, v67
	v_max3_f32 v66, v60, v61, v66
	v_max3_f32 v67, v56, v57, v67
	v_max3_f32 v66, v66, s20, v67
	v_max_f32_e32 v67, v55, v55
	v_max_f32_e32 v68, v54, v54
	v_max_f32_e32 v67, v68, v67
	v_max_f32_e32 v68, v51, v51
	v_max_f32_e32 v69, v50, v50
	v_max_f32_e32 v68, v69, v68
	v_max3_f32 v67, v52, v53, v67
	v_max3_f32 v68, v48, v49, v68
	v_max3_f32 v66, v66, v67, v68
	v_max_f32_e32 v67, v47, v47
	v_max_f32_e32 v68, v46, v46
	v_max_f32_e32 v67, v68, v67
	v_max_f32_e32 v68, v43, v43
	v_max_f32_e32 v69, v42, v42
	v_max_f32_e32 v68, v69, v68
	v_max3_f32 v67, v44, v45, v67
	v_max3_f32 v68, v40, v41, v68
	v_max3_f32 v66, v66, v67, v68
	v_max_f32_e32 v67, v39, v39
	v_max_f32_e32 v68, v38, v38
	v_max_f32_e32 v67, v68, v67
	v_max_f32_e32 v68, v35, v35
	v_max_f32_e32 v69, v34, v34
	v_max_f32_e32 v68, v69, v68
	v_max3_f32 v67, v36, v37, v67
	v_max3_f32 v68, v32, v33, v68
	v_max3_f32 v66, v66, v67, v68
	v_max_f32_e32 v67, v31, v31
	v_max_f32_e32 v68, v30, v30
	v_max_f32_e32 v67, v68, v67
	v_max_f32_e32 v68, v27, v27
	v_max_f32_e32 v69, v26, v26
	v_max_f32_e32 v68, v69, v68
	v_max3_f32 v67, v28, v29, v67
	v_max3_f32 v68, v24, v25, v68
	v_max3_f32 v66, v66, v67, v68
	v_max_f32_e32 v67, v23, v23
	v_max_f32_e32 v68, v22, v22
	v_max_f32_e32 v67, v68, v67
	v_max_f32_e32 v68, v19, v19
	v_max_f32_e32 v69, v18, v18
	v_max_f32_e32 v68, v69, v68
	v_max3_f32 v67, v20, v21, v67
	v_max3_f32 v68, v16, v17, v68
	v_max3_f32 v66, v66, v67, v68
	v_max_f32_e32 v67, v15, v15
	v_max_f32_e32 v68, v14, v14
	v_max_f32_e32 v67, v68, v67
	v_max_f32_e32 v68, v11, v11
	v_max_f32_e32 v69, v10, v10
	v_max_f32_e32 v68, v69, v68
	v_max3_f32 v67, v12, v13, v67
	v_max3_f32 v68, v8, v9, v68
	v_max3_f32 v66, v66, v67, v68
	v_max_f32_e32 v67, v7, v7
	v_max_f32_e32 v68, v6, v6
	v_max_f32_e32 v67, v68, v67
	v_max_f32_e32 v68, v3, v3
	v_max_f32_e32 v69, v2, v2
	v_max_f32_e32 v68, v69, v68
	v_max3_f32 v67, v4, v5, v67
	v_max3_f32 v68, v0, v1, v68
	v_max3_f32 v66, v66, v67, v68
	v_and_b32_e32 v68, 64, v192
	v_xor_b32_e32 v67, 16, v192
	v_add_u32_e32 v68, 64, v68
	v_cmp_lt_i32_e32 vcc, v67, v68
	s_mov_b64 s[20:21], 0x1700
	s_nop 0
	v_cndmask_b32_e32 v67, v192, v67, vcc
	v_lshlrev_b32_e32 v69, 2, v67
	ds_bpermute_b32 v67, v69, v66
	s_waitcnt lgkmcnt(0)
	v_max_f32_e32 v67, v67, v67
	v_max_f32_e32 v67, v66, v67
	v_xor_b32_e32 v66, 32, v192
	v_cmp_lt_i32_e32 vcc, v66, v68
	s_nop 1
	v_cndmask_b32_e32 v66, v192, v66, vcc
	v_lshlrev_b32_e32 v68, 2, v66
	ds_bpermute_b32 v76, v68, v67
	v_lshlrev_b32_e32 v66, 3, v71
	s_waitcnt lgkmcnt(0)
	v_max_f32_e32 v71, v76, v76
	v_max_f32_e32 v71, v67, v71
	v_sub_f32_e32 v60, v60, v71
	v_mul_f32_e32 v60, 0x3e000000, v60
	v_mul_f32_e32 v60, 0x3fb8aa3b, v60
	v_exp_f32_e32 v78, v60
	v_sub_f32_e32 v60, v61, v71
	v_sub_f32_e32 v56, v56, v71
	v_mul_f32_e32 v60, 0x3e000000, v60
	v_mul_f32_e32 v56, 0x3e000000, v56
	v_mul_f32_e32 v60, 0x3fb8aa3b, v60
	v_mul_f32_e32 v56, 0x3fb8aa3b, v56
	v_exp_f32_e32 v79, v60
	v_sub_f32_e32 v60, v62, v71
	v_exp_f32_e32 v80, v56
	v_sub_f32_e32 v56, v57, v71
	v_sub_f32_e32 v52, v52, v71
	v_mul_f32_e32 v60, 0x3e000000, v60
	v_mul_f32_e32 v56, 0x3e000000, v56
	v_mul_f32_e32 v52, 0x3e000000, v52
	v_mul_f32_e32 v60, 0x3fb8aa3b, v60
	v_mul_f32_e32 v56, 0x3fb8aa3b, v56
	v_mul_f32_e32 v52, 0x3fb8aa3b, v52
	v_exp_f32_e32 v62, v60
	v_sub_f32_e32 v60, v63, v71
	v_exp_f32_e32 v81, v56
	v_sub_f32_e32 v56, v58, v71
	v_exp_f32_e32 v94, v52
	v_sub_f32_e32 v52, v53, v71
	v_mul_f32_e32 v60, 0x3e000000, v60
	v_mul_f32_e32 v56, 0x3e000000, v56
	v_mul_f32_e32 v52, 0x3e000000, v52
	v_mul_f32_e32 v60, 0x3fb8aa3b, v60
	v_mul_f32_e32 v56, 0x3fb8aa3b, v56
	v_mul_f32_e32 v52, 0x3fb8aa3b, v52
	v_exp_f32_e32 v63, v60
	v_exp_f32_e32 v86, v56
	v_sub_f32_e32 v56, v59, v71
	v_exp_f32_e32 v95, v52
	v_sub_f32_e32 v52, v54, v71
	v_sub_f32_e32 v40, v40, v71
	v_mul_f32_e32 v56, 0x3e000000, v56
	v_mul_f32_e32 v52, 0x3e000000, v52
	v_sub_f32_e32 v48, v48, v71
	v_mul_f32_e32 v40, 0x3e000000, v40
	v_add_f32_e32 v60, v78, v79
	v_mul_f32_e32 v56, 0x3fb8aa3b, v56
	v_mul_f32_e32 v52, 0x3fb8aa3b, v52
	v_mul_f32_e32 v48, 0x3e000000, v48
	v_mul_f32_e32 v40, 0x3fb8aa3b, v40
	v_add_f32_e32 v60, v62, v60
	v_exp_f32_e32 v59, v56
	v_exp_f32_e32 v98, v52
	v_sub_f32_e32 v52, v55, v71
	v_mul_f32_e32 v48, 0x3fb8aa3b, v48
	v_exp_f32_e32 v103, v40
	v_sub_f32_e32 v40, v41, v71
	v_add_f32_e32 v61, v63, v60
	v_mul_f32_e32 v52, 0x3e000000, v52
	v_exp_f32_e32 v60, v48
	v_sub_f32_e32 v48, v49, v71
	v_mul_f32_e32 v40, 0x3e000000, v40
	v_add_f32_e32 v56, v80, v81
	v_mul_f32_e32 v52, 0x3fb8aa3b, v52
	v_mul_f32_e32 v48, 0x3e000000, v48
	v_mul_f32_e32 v40, 0x3fb8aa3b, v40
	v_add_f32_e32 v56, v86, v56
	v_exp_f32_e32 v99, v52
	v_mul_f32_e32 v48, 0x3fb8aa3b, v48
	v_exp_f32_e32 v104, v40
	v_sub_f32_e32 v40, v42, v71
	v_add_f32_e32 v53, v59, v56
	v_exp_f32_e32 v56, v48
	v_sub_f32_e32 v48, v50, v71
	v_mul_f32_e32 v40, 0x3e000000, v40
	v_add_f32_e32 v52, v94, v95
	v_mul_f32_e32 v48, 0x3e000000, v48
	v_sub_f32_e32 v44, v44, v71
	v_mul_f32_e32 v40, 0x3fb8aa3b, v40
	v_add_f32_e32 v52, v98, v52
	v_mul_f32_e32 v48, 0x3fb8aa3b, v48
	v_mul_f32_e32 v44, 0x3e000000, v44
	v_exp_f32_e32 v105, v40
	v_sub_f32_e32 v40, v43, v71
	v_add_f32_e32 v55, v99, v52
	v_exp_f32_e32 v52, v48
	v_sub_f32_e32 v48, v51, v71
	v_mul_f32_e32 v44, 0x3fb8aa3b, v44
	v_mul_f32_e32 v40, 0x3e000000, v40
	v_mul_f32_e32 v48, 0x3e000000, v48
	v_exp_f32_e32 v100, v44
	v_sub_f32_e32 v44, v45, v71
	v_mul_f32_e32 v40, 0x3fb8aa3b, v40
	v_mul_f32_e32 v48, 0x3fb8aa3b, v48
	v_mul_f32_e32 v44, 0x3e000000, v44
	v_exp_f32_e32 v106, v40
	v_exp_f32_e32 v54, v48
	v_mul_f32_e32 v44, 0x3fb8aa3b, v44
	v_sub_f32_e32 v32, v32, v71
	v_mov_b32_e32 v57, v65
	v_exp_f32_e32 v45, v44
	v_sub_f32_e32 v44, v46, v71
	v_add_f32_e32 v40, v103, v104
	v_mul_f32_e32 v32, 0x3e000000, v32
	v_pk_add_f32 v[48:49], v[60:61], v[56:57]
	v_mul_f32_e32 v44, 0x3e000000, v44
	v_add_f32_e32 v40, v105, v40
	v_mul_f32_e32 v32, 0x3fb8aa3b, v32
	v_pk_add_f32 v[48:49], v[52:53], v[48:49]
	v_mul_f32_e32 v44, 0x3fb8aa3b, v44
	v_add_f32_e32 v43, v106, v40
	v_exp_f32_e32 v40, v32
	v_sub_f32_e32 v32, v33, v71
	v_pk_add_f32 v[48:49], v[54:55], v[48:49]
	v_exp_f32_e32 v101, v44
	v_sub_f32_e32 v44, v47, v71
	v_mul_f32_e32 v32, 0x3e000000, v32
	v_pk_add_f32 v[48:49], v[48:49], v[48:49] op_sel_hi:[0,1]
	v_mul_f32_e32 v44, 0x3e000000, v44
	v_mul_f32_e32 v32, 0x3fb8aa3b, v32
	v_mul_f32_e32 v44, 0x3fb8aa3b, v44
	v_sub_f32_e32 v36, v36, v71
	v_exp_f32_e32 v48, v32
	v_sub_f32_e32 v32, v34, v71
	v_sub_f32_e32 v24, v24, v71
	v_exp_f32_e32 v102, v44
	v_mul_f32_e32 v36, 0x3e000000, v36
	v_mul_f32_e32 v32, 0x3e000000, v32
	v_mul_f32_e32 v24, 0x3e000000, v24
	v_mul_f32_e32 v36, 0x3fb8aa3b, v36
	v_mul_f32_e32 v32, 0x3fb8aa3b, v32
	v_mul_f32_e32 v24, 0x3fb8aa3b, v24
	v_add_f32_e32 v44, v100, v45
	v_exp_f32_e32 v57, v36
	v_sub_f32_e32 v36, v37, v71
	v_exp_f32_e32 v42, v32
	v_sub_f32_e32 v32, v35, v71
	v_exp_f32_e32 v47, v24
	v_sub_f32_e32 v24, v25, v71
	v_add_f32_e32 v44, v101, v44
	v_mul_f32_e32 v36, 0x3e000000, v36
	v_mul_f32_e32 v32, 0x3e000000, v32
	v_sub_f32_e32 v28, v28, v71
	v_mul_f32_e32 v24, 0x3e000000, v24
	v_add_f32_e32 v41, v102, v44
	v_mul_f32_e32 v36, 0x3fb8aa3b, v36
	v_mul_f32_e32 v32, 0x3fb8aa3b, v32
	v_mul_f32_e32 v28, 0x3e000000, v28
	v_mul_f32_e32 v24, 0x3fb8aa3b, v24
	v_exp_f32_e32 v58, v36
	v_sub_f32_e32 v36, v38, v71
	v_exp_f32_e32 v34, v32
	v_pk_add_f32 v[32:33], v[40:41], v[48:49]
	v_mul_f32_e32 v28, 0x3fb8aa3b, v28
	v_exp_f32_e32 v49, v24
	v_sub_f32_e32 v24, v26, v71
	v_mul_f32_e32 v36, 0x3e000000, v36
	v_pk_add_f32 v[32:33], v[42:43], v[32:33]
	v_exp_f32_e32 v43, v28
	v_sub_f32_e32 v28, v29, v71
	v_mul_f32_e32 v24, 0x3e000000, v24
	v_mul_f32_e32 v36, 0x3fb8aa3b, v36
	v_mul_f32_e32 v28, 0x3e000000, v28
	v_mul_f32_e32 v24, 0x3fb8aa3b, v24
	v_exp_f32_e32 v53, v36
	v_sub_f32_e32 v36, v39, v71
	v_mul_f32_e32 v28, 0x3fb8aa3b, v28
	v_exp_f32_e32 v50, v24
	v_sub_f32_e32 v24, v27, v71
	v_mul_f32_e32 v36, 0x3e000000, v36
	v_exp_f32_e32 v46, v28
	v_sub_f32_e32 v28, v30, v71
	v_mul_f32_e32 v24, 0x3e000000, v24
	v_mul_f32_e32 v36, 0x3fb8aa3b, v36
	v_mul_f32_e32 v28, 0x3e000000, v28
	v_sub_f32_e32 v29, v31, v71
	v_mul_f32_e32 v24, 0x3fb8aa3b, v24
	v_exp_f32_e32 v55, v36
	v_mul_f32_e32 v28, 0x3fb8aa3b, v28
	v_mul_f32_e32 v29, 0x3e000000, v29
	v_exp_f32_e32 v51, v24
	v_exp_f32_e32 v28, v28
	v_mul_f32_e32 v29, 0x3fb8aa3b, v29
	v_sub_f32_e32 v16, v16, v71
	v_add_f32_e32 v36, v57, v58
	v_exp_f32_e32 v29, v29
	v_add_f32_e32 v24, v47, v49
	v_mul_f32_e32 v16, 0x3e000000, v16
	v_add_f32_e32 v36, v53, v36
	v_add_f32_e32 v24, v50, v24
	v_sub_f32_e32 v21, v21, v71
	v_mul_f32_e32 v16, 0x3fb8aa3b, v16
	v_add_f32_e32 v35, v55, v36
	v_add_f32_e32 v30, v43, v46
	v_add_f32_e32 v27, v51, v24
	v_mul_f32_e32 v21, 0x3e000000, v21
	v_exp_f32_e32 v24, v16
	v_sub_f32_e32 v16, v17, v71
	v_pk_add_f32 v[32:33], v[34:35], v[32:33]
	v_add_f32_e32 v30, v28, v30
	v_mul_f32_e32 v21, 0x3fb8aa3b, v21
	v_mul_f32_e32 v16, 0x3e000000, v16
	v_pk_add_f32 v[32:33], v[32:33], v[32:33] op_sel_hi:[0,1]
	v_add_f32_e32 v25, v29, v30
	v_exp_f32_e32 v30, v21
	v_sub_f32_e32 v21, v22, v71
	v_mul_f32_e32 v16, 0x3fb8aa3b, v16
	v_sub_f32_e32 v20, v20, v71
	v_mul_f32_e32 v21, 0x3e000000, v21
	v_exp_f32_e32 v32, v16
	v_sub_f32_e32 v16, v18, v71
	v_mul_f32_e32 v20, 0x3e000000, v20
	v_mul_f32_e32 v21, 0x3fb8aa3b, v21
	v_mul_f32_e32 v16, 0x3e000000, v16
	v_mul_f32_e32 v20, 0x3fb8aa3b, v20
	v_exp_f32_e32 v22, v21
	v_sub_f32_e32 v21, v23, v71
	v_mul_f32_e32 v16, 0x3fb8aa3b, v16
	v_exp_f32_e32 v20, v20
	v_mul_f32_e32 v21, 0x3e000000, v21
	v_exp_f32_e32 v26, v16
	v_sub_f32_e32 v16, v19, v71
	v_mul_f32_e32 v21, 0x3fb8aa3b, v21
	v_mul_f32_e32 v16, 0x3e000000, v16
	v_exp_f32_e32 v23, v21
	v_mul_f32_e32 v16, 0x3fb8aa3b, v16
	v_exp_f32_e32 v16, v16
	v_add_f32_e32 v21, v20, v30
	v_sub_f32_e32 v12, v12, v71
	v_add_f32_e32 v21, v22, v21
	v_pk_add_f32 v[18:19], v[24:25], v[32:33]
	v_mul_f32_e32 v12, 0x3e000000, v12
	v_add_f32_e32 v17, v23, v21
	v_pk_add_f32 v[18:19], v[26:27], v[18:19]
	v_mul_f32_e32 v12, 0x3fb8aa3b, v12
	v_pk_add_f32 v[36:37], v[16:17], v[18:19]
	v_exp_f32_e32 v18, v12
	v_sub_f32_e32 v12, v13, v71
	v_mul_f32_e32 v12, 0x3e000000, v12
	v_mul_f32_e32 v12, 0x3fb8aa3b, v12
	v_exp_f32_e32 v19, v12
	v_sub_f32_e32 v12, v14, v71
	v_mul_f32_e32 v12, 0x3e000000, v12
	v_sub_f32_e32 v8, v8, v71
	v_mul_f32_e32 v12, 0x3fb8aa3b, v12
	v_mul_f32_e32 v8, 0x3e000000, v8
	v_exp_f32_e32 v25, v12
	v_sub_f32_e32 v12, v15, v71
	v_mul_f32_e32 v8, 0x3fb8aa3b, v8
	v_mul_f32_e32 v12, 0x3e000000, v12
	v_exp_f32_e32 v33, v8
	v_sub_f32_e32 v8, v9, v71
	v_sub_u32_e32 v9, v75, v66
	v_mul_f32_e32 v12, 0x3fb8aa3b, v12
	v_mad_u32_u24 v9, v74, s26, v9
	v_exp_f32_e32 v27, v12
	v_pk_add_f32 v[12:13], v[36:37], v[36:37] op_sel_hi:[0,1]
	v_add_u32_e32 v39, 0x9000, v9
	v_add_u32_e32 v31, 0xb000, v9
	v_add_u32_e32 v35, 0xd000, v9
	v_add_u32_e32 v37, 0xf000, v9
	ds_read2_b64 v[74:77], v39 offset1:4
	ds_read2_b64 v[82:85], v31 offset0:32 offset1:36
	v_cvt_pk_bf16_f32 v80, v80, v81
	v_cvt_pk_bf16_f32 v81, v86, v59
	ds_read2_b64 v[86:89], v35 offset0:64 offset1:68
	ds_read2_b64 v[90:93], v37 offset0:96 offset1:100
	v_mul_f32_e32 v8, 0x3e000000, v8
	v_mul_f32_e32 v8, 0x3fb8aa3b, v8
	v_exp_f32_e32 v36, v8
	v_sub_f32_e32 v8, v10, v71
	v_mul_f32_e32 v8, 0x3e000000, v8
	v_mul_f32_e32 v8, 0x3fb8aa3b, v8
	v_add_f32_e32 v12, v18, v19
	v_exp_f32_e32 v41, v8
	v_sub_f32_e32 v8, v11, v71
	v_add_f32_e32 v12, v25, v12
	v_cvt_pk_bf16_f32 v78, v78, v79
	v_cvt_pk_bf16_f32 v79, v62, v63
	v_mul_f32_e32 v8, 0x3e000000, v8
	v_add_f32_e32 v15, v27, v12
	s_waitcnt lgkmcnt(3)
	v_mfma_f32_16x16x32_bf16 v[74:77], v[74:77], v[78:81], 0
	v_mul_f32_e32 v12, 0x3fb8aa3b, v8
	v_sub_f32_e32 v4, v4, v71
	v_mul_f32_e32 v4, 0x3e000000, v4
	s_waitcnt lgkmcnt(2)
	v_mfma_f32_16x16x32_bf16 v[82:85], v[82:85], v[78:81], 0
	v_mul_f32_e32 v4, 0x3fb8aa3b, v4
	v_exp_f32_e32 v38, v4
	v_sub_f32_e32 v4, v5, v71
	s_waitcnt lgkmcnt(1)
	v_mfma_f32_16x16x32_bf16 v[8:11], v[86:89], v[78:81], 0
	ds_read2_b64 v[86:89], v39 offset0:8 offset1:12
	v_mul_f32_e32 v4, 0x3e000000, v4
	v_mul_f32_e32 v4, 0x3fb8aa3b, v4
	s_waitcnt lgkmcnt(1)
	v_mfma_f32_16x16x32_bf16 v[78:81], v[90:93], v[78:81], 0
	v_cvt_pk_bf16_f32 v92, v60, v56
	ds_read2_b64 v[60:63], v35 offset0:72 offset1:76
	v_cvt_pk_bf16_f32 v90, v94, v95
	ds_read2_b64 v[94:97], v31 offset0:40 offset1:44
	v_cvt_pk_bf16_f32 v91, v98, v99
	v_cvt_pk_bf16_f32 v93, v52, v54
	v_exp_f32_e32 v44, v12
	s_waitcnt lgkmcnt(2)
	v_mfma_f32_16x16x32_bf16 v[74:77], v[86:89], v[90:93], v[74:77]
	ds_read2_b64 v[86:89], v37 offset0:104 offset1:108
	v_add_f32_e32 v12, v33, v36
	v_add_f32_e32 v12, v41, v12
	s_waitcnt lgkmcnt(2)
	v_mfma_f32_16x16x32_bf16 v[8:11], v[60:63], v[90:93], v[8:11]
	ds_read2_b64 v[60:63], v39 offset0:16 offset1:20
	v_sub_f32_e32 v0, v0, v71
	v_add_f32_e32 v17, v44, v12
	s_waitcnt lgkmcnt(2)
	v_mfma_f32_16x16x32_bf16 v[82:85], v[94:97], v[90:93], v[82:85]
	ds_read2_b64 v[94:97], v35 offset0:80 offset1:84
	v_mul_f32_e32 v0, 0x3e000000, v0
	v_mov_b32_e32 v67, v65
	s_waitcnt lgkmcnt(2)
	v_mfma_f32_16x16x32_bf16 v[78:81], v[86:89], v[90:93], v[78:81]
	v_cvt_pk_bf16_f32 v86, v100, v45
	ds_read2_b64 v[90:93], v31 offset0:48 offset1:52
	v_cvt_pk_bf16_f32 v87, v101, v102
	v_cvt_pk_bf16_f32 v88, v103, v104
	v_cvt_pk_bf16_f32 v89, v105, v106
	v_exp_f32_e32 v45, v4
	s_waitcnt lgkmcnt(2)
	v_mfma_f32_16x16x32_bf16 v[60:63], v[60:63], v[86:89], v[74:77]
	v_sub_f32_e32 v4, v6, v71
	v_mul_f32_e32 v4, 0x3e000000, v4
	v_mul_f32_e32 v4, 0x3fb8aa3b, v4
	ds_read2_b64 v[74:77], v37 offset0:112 offset1:116
	s_waitcnt lgkmcnt(1)
	v_mfma_f32_16x16x32_bf16 v[82:85], v[90:93], v[86:89], v[82:85]
	v_exp_f32_e32 v52, v4
	v_sub_f32_e32 v4, v7, v71
	v_mul_f32_e32 v12, 0x3e000000, v4
	v_mfma_f32_16x16x32_bf16 v[8:11], v[94:97], v[86:89], v[8:11]
	v_mul_f32_e32 v12, 0x3fb8aa3b, v12
	v_mul_f32_e32 v0, 0x3fb8aa3b, v0
	v_cvt_pk_bf16_f32 v54, v57, v58
	s_waitcnt lgkmcnt(0)
	v_mfma_f32_16x16x32_bf16 v[74:77], v[74:77], v[86:89], v[78:81]
	ds_read2_b64 v[86:89], v35 offset0:88 offset1:92
	v_cvt_pk_bf16_f32 v55, v53, v55
	v_cvt_pk_bf16_f32 v56, v40, v48
	v_cvt_pk_bf16_f32 v57, v42, v34
	v_exp_f32_e32 v34, v12
	s_nop 0
	ds_read2_b64 v[78:81], v31 offset0:56 offset1:60
	s_waitcnt lgkmcnt(0)
	v_mfma_f32_16x16x32_bf16 v[78:81], v[78:81], v[54:57], v[82:85]
	v_add_f32_e32 v12, v38, v45
	v_exp_f32_e32 v14, v0
	v_sub_f32_e32 v0, v1, v71
	v_mfma_f32_16x16x32_bf16 v[82:85], v[86:89], v[54:57], v[8:11]
	v_cvt_pk_bf16_f32 v11, v50, v51
	v_lshl_add_u64 v[50:51], v[72:73], 0, v[66:67]
	ds_read2_b64 v[90:93], v39 offset0:24 offset1:28
	ds_read2_b64 v[4:7], v37 offset0:120 offset1:124
	v_add_f32_e32 v8, v52, v12
	v_mul_f32_e32 v12, 0x3e000000, v0
	v_add_co_u32_e32 v0, vcc, s2, v50
	v_cvt_pk_bf16_f32 v9, v28, v29
	s_waitcnt lgkmcnt(1)
	v_mfma_f32_16x16x32_bf16 v[58:61], v[90:93], v[54:57], v[60:63]
	v_addc_co_u32_e32 v1, vcc, 0, v51, vcc
	global_load_dwordx2 v[28:29], v[0:1], off offset:1792
	s_waitcnt lgkmcnt(0)
	v_mfma_f32_16x16x32_bf16 v[4:7], v[4:7], v[54:57], v[74:77]
	ds_read2_b64 v[54:57], v31 offset0:64 offset1:68
	ds_read2_b64 v[86:89], v39 offset0:32 offset1:36
	v_add_f32_e32 v21, v34, v8
	v_cvt_pk_bf16_f32 v8, v43, v46
	v_cvt_pk_bf16_f32 v10, v47, v49
	ds_read2_b64 v[46:49], v35 offset0:96 offset1:100
	s_waitcnt lgkmcnt(2)
	v_mfma_f32_16x16x32_bf16 v[54:57], v[54:57], v[8:11], v[78:81]
	ds_read2_b64 v[74:77], v37 offset0:128 offset1:132
	s_nop 1
	ds_read2_b64 v[78:81], v39 offset0:40 offset1:44
	v_mul_f32_e32 v0, 0x3fb8aa3b, v12
	s_waitcnt lgkmcnt(3)
	v_mfma_f32_16x16x32_bf16 v[58:61], v[86:89], v[8:11], v[58:61]
	v_exp_f32_e32 v12, v0
	v_sub_f32_e32 v0, v2, v71
	v_mul_f32_e32 v0, 0x3e000000, v0
	s_waitcnt lgkmcnt(2)
	v_mfma_f32_16x16x32_bf16 v[46:49], v[46:49], v[8:11], v[82:85]
	v_mul_f32_e32 v0, 0x3fb8aa3b, v0
	s_mov_b32 s2, 0x4580000
	s_waitcnt lgkmcnt(1)
	v_mfma_f32_16x16x32_bf16 v[4:7], v[74:77], v[8:11], v[4:7]
	v_cvt_pk_bf16_f32 v8, v20, v30
	ds_read2_b64 v[72:75], v31 offset0:72 offset1:76
	v_cvt_pk_bf16_f32 v9, v22, v23
	v_cvt_pk_bf16_f32 v10, v24, v32
	v_cvt_pk_bf16_f32 v11, v26, v16
	ds_read2_b64 v[82:85], v35 offset0:104 offset1:108
	s_waitcnt lgkmcnt(2)
	v_mfma_f32_16x16x32_bf16 v[58:61], v[78:81], v[8:11], v[58:61]
	ds_read2_b64 v[76:79], v37 offset0:136 offset1:140
	v_exp_f32_e32 v16, v0
	v_sub_f32_e32 v0, v3, v71
	s_waitcnt lgkmcnt(2)
	v_mfma_f32_16x16x32_bf16 v[54:57], v[72:75], v[8:11], v[54:57]
	v_mul_f32_e32 v20, 0x3e000000, v0
	ds_read2_b64 v[72:75], v39 offset0:48 offset1:52
	v_cvt_pk_bf16_f32 v32, v14, v12
	s_waitcnt lgkmcnt(2)
	v_mfma_f32_16x16x32_bf16 v[46:49], v[82:85], v[8:11], v[46:49]
	v_cvt_pk_bf16_f32 v30, v38, v45
	v_ashrrev_i32_e32 v71, 31, v70
	s_waitcnt lgkmcnt(1)
	v_mfma_f32_16x16x32_bf16 v[0:3], v[76:79], v[8:11], v[4:7]
	ds_read2_b64 v[8:11], v31 offset0:80 offset1:84
	v_cvt_pk_bf16_f32 v4, v18, v19
	v_mul_f32_e32 v18, 0x3fb8aa3b, v20
	v_exp_f32_e32 v20, v18
	v_pk_add_f32 v[18:19], v[14:15], v[12:13]
	v_cvt_pk_bf16_f32 v5, v25, v27
	v_cvt_pk_bf16_f32 v6, v33, v36
	v_cvt_pk_bf16_f32 v7, v41, v44
	ds_read2_b64 v[40:43], v35 offset0:112 offset1:116
	s_waitcnt lgkmcnt(1)
	v_mfma_f32_16x16x32_bf16 v[8:11], v[8:11], v[4:7], v[54:57]
	v_add_f32_e64 v18, v16, v18
	v_add_f32_e64 v19, v17, v19
	ds_read2_b64 v[12:15], v35 offset0:120 offset1:124
	v_pk_add_f32 v[18:19], v[20:21], v[18:19]
	ds_read2_b64 v[54:57], v37 offset0:144 offset1:148
	v_add_f32_e32 v17, v18, v19
	v_lshl_add_u64 v[18:19], v[50:51], 0, s[20:21]
	global_load_dwordx2 v[22:23], v[18:19], off offset:32
	ds_bpermute_b32 v21, v69, v17
	v_mfma_f32_16x16x32_bf16 v[24:27], v[72:75], v[4:7], v[58:61]
	v_cvt_pk_bf16_f32 v33, v16, v20
	s_waitcnt lgkmcnt(0)
	v_add_f32_e32 v16, v17, v21
	v_mfma_f32_16x16x32_bf16 v[40:43], v[40:43], v[4:7], v[46:49]
	ds_bpermute_b32 v17, v68, v16
	s_waitcnt lgkmcnt(0)
	v_add_f32_e32 v16, v16, v17
	v_mfma_f32_16x16x32_bf16 v[0:3], v[54:57], v[4:7], v[0:3]
	ds_read2_b64 v[4:7], v31 offset0:88 offset1:92
	v_cvt_pk_bf16_f32 v31, v52, v34
	ds_read2_b64 v[46:49], v39 offset0:56 offset1:60
	s_waitcnt lgkmcnt(1)
	v_mfma_f32_16x16x32_bf16 v[8:11], v[4:7], v[30:33], v[8:11]
	ds_read2_b64 v[34:37], v37 offset0:152 offset1:156
	v_mfma_f32_16x16x32_bf16 v[4:7], v[12:15], v[30:33], v[40:43]
	v_div_scale_f32 v12, s[20:21], v16, v16, 1.0
	v_rcp_f32_e32 v13, v12
	s_waitcnt lgkmcnt(1)
	v_mfma_f32_16x16x32_bf16 v[24:27], v[46:49], v[30:33], v[24:27]
	s_mov_b64 s[20:21], 0x4580600
	v_fma_f32 v14, -v12, v13, 1.0
	v_fmac_f32_e32 v13, v14, v13
	v_div_scale_f32 v14, vcc, 1.0, v16, 1.0
	v_mul_f32_e32 v15, v14, v13
	v_fma_f32 v17, -v12, v15, v14
	v_fmac_f32_e32 v15, v17, v13
	v_fma_f32 v12, -v12, v15, v14
	v_div_fmas_f32 v12, v12, v13, v15
	global_load_dwordx2 v[14:15], v[18:19], off offset:64
	v_div_fixup_f32 v12, v12, v16, 1.0
	v_lshlrev_b64 v[16:17], 11, v[70:71]
	v_lshl_add_u64 v[16:17], s[94:95], 0, v[16:17]
	v_lshl_add_u64 v[20:21], v[16:17], 0, v[64:65]
	s_waitcnt vmcnt(2)
	v_lshlrev_b32_e32 v17, 16, v28
	v_mul_f32_e32 v13, 0xbfb8aa3b, v17
	v_exp_f32_e32 v13, v13
	s_waitcnt lgkmcnt(0)
	v_mfma_f32_16x16x32_bf16 v[0:3], v[34:37], v[30:33], v[0:3]
	v_and_b32_e32 v31, 0xffff0000, v28
	v_mul_f32_e32 v16, 0xbfb8aa3b, v31
	v_add_f32_e32 v13, 1.0, v13
	v_rcp_f32_e32 v13, v13
	v_exp_f32_e32 v28, v16
	v_mov_b32_e32 v16, v24
	v_lshlrev_b32_e32 v33, 16, v29
	v_pk_mul_f32 v[16:17], v[12:13], v[16:17]
	v_add_f32_e32 v13, 1.0, v28
	v_mul_f32_e32 v24, v16, v17
	v_mul_f32_e32 v16, 0xbfb8aa3b, v33
	v_rcp_f32_e32 v13, v13
	v_exp_f32_e32 v28, v16
	v_mov_b32_e32 v30, v25
	v_and_b32_e32 v29, 0xffff0000, v29
	v_pk_mul_f32 v[16:17], v[12:13], v[30:31]
	v_add_f32_e32 v13, 1.0, v28
	v_mul_f32_e32 v16, v16, v17
	v_rcp_f32_e32 v13, v13
	v_mul_f32_e32 v17, 0xbfb8aa3b, v29
	v_exp_f32_e32 v25, v17
	v_mov_b32_e32 v32, v26
	v_cvt_pk_bf16_f32 v24, v24, v16
	v_pk_mul_f32 v[16:17], v[12:13], v[32:33]
	v_add_f32_e32 v13, 1.0, v25
	v_mul_f32_e32 v25, v16, v17
	global_load_dwordx2 v[16:17], v[18:19], off offset:96
	v_rcp_f32_e32 v13, v13
	v_mov_b32_e32 v28, v27
	s_waitcnt vmcnt(2)
	v_lshlrev_b32_e32 v27, 16, v22
	v_lshl_add_u64 v[20:21], v[20:21], 0, v[66:67]
	v_pk_mul_f32 v[18:19], v[12:13], v[28:29]
	v_mov_b32_e32 v26, v8
	v_mul_f32_e32 v13, v18, v19
	v_cvt_pk_bf16_f32 v25, v25, v13
	v_mul_f32_e32 v13, 0xbfb8aa3b, v27
	v_lshl_add_u64 v[18:19], v[20:21], 0, s[20:21]
	v_add_co_u32_e32 v20, vcc, s2, v20
	v_exp_f32_e32 v13, v13
	s_nop 0
	v_addc_co_u32_e32 v21, vcc, 0, v21, vcc
	global_store_dwordx2 v[20:21], v[24:25], off offset:1536
	v_and_b32_e32 v21, 0xffff0000, v22
	v_mul_f32_e32 v20, 0xbfb8aa3b, v21
	v_add_f32_e32 v13, 1.0, v13
	v_exp_f32_e32 v20, v20
	v_rcp_f32_e32 v13, v13
	v_lshlrev_b32_e32 v25, 16, v23
	v_and_b32_e32 v23, 0xffff0000, v23
	v_add_f32_e32 v8, 1.0, v20
	v_pk_mul_f32 v[26:27], v[12:13], v[26:27]
	v_rcp_f32_e32 v13, v8
	v_mul_f32_e32 v8, 0xbfb8aa3b, v25
	v_exp_f32_e32 v22, v8
	v_mov_b32_e32 v20, v9
	v_pk_mul_f32 v[8:9], v[12:13], v[20:21]
	v_mul_f32_e32 v20, 0xbfb8aa3b, v23
	v_add_f32_e32 v13, 1.0, v22
	v_exp_f32_e32 v20, v20
	v_rcp_f32_e32 v13, v13
	v_mov_b32_e32 v24, v10
	v_mul_f32_e32 v21, v8, v9
	v_add_f32_e32 v10, 1.0, v20
	v_pk_mul_f32 v[8:9], v[12:13], v[24:25]
	v_rcp_f32_e32 v13, v10
	v_mov_b32_e32 v22, v11
	v_mul_f32_e32 v20, v8, v9
	v_mul_f32_e32 v26, v26, v27
	v_pk_mul_f32 v[8:9], v[12:13], v[22:23]
	v_cvt_pk_bf16_f32 v10, v26, v21
	s_waitcnt vmcnt(2)
	v_lshlrev_b32_e32 v21, 16, v15
	v_mul_f32_e32 v8, v8, v9
	v_lshlrev_b32_e32 v9, 16, v14
	v_cvt_pk_bf16_f32 v11, v20, v8
	v_mul_f32_e32 v8, 0xbfb8aa3b, v9
	v_exp_f32_e32 v8, v8
	global_store_dwordx2 v[18:19], v[10:11], off offset:32
	v_and_b32_e32 v11, 0xffff0000, v14
	v_and_b32_e32 v15, 0xffff0000, v15
	v_add_f32_e32 v8, 1.0, v8
	v_rcp_f32_e32 v13, v8
	v_mul_f32_e32 v8, 0xbfb8aa3b, v11
	v_exp_f32_e32 v10, v8
	v_mov_b32_e32 v8, v4
	v_pk_mul_f32 v[8:9], v[12:13], v[8:9]
	v_mov_b32_e32 v20, v6
	v_add_f32_e32 v4, 1.0, v10
	v_rcp_f32_e32 v13, v4
	v_mul_f32_e32 v4, 0xbfb8aa3b, v21
	v_exp_f32_e32 v14, v4
	v_mul_f32_e32 v8, v8, v9
	v_mov_b32_e32 v10, v5
	v_pk_mul_f32 v[4:5], v[12:13], v[10:11]
	v_add_f32_e32 v9, 1.0, v14
	v_rcp_f32_e32 v13, v9
	v_mul_f32_e32 v9, 0xbfb8aa3b, v15
	v_exp_f32_e32 v9, v9
	v_mul_f32_e32 v10, v4, v5
	v_pk_mul_f32 v[4:5], v[12:13], v[20:21]
	v_mov_b32_e32 v14, v7
	v_add_f32_e32 v6, 1.0, v9
	v_rcp_f32_e32 v13, v6
	v_cvt_pk_bf16_f32 v6, v8, v10
	v_mul_f32_e32 v8, v4, v5
	v_mov_b32_e32 v10, v3
	v_pk_mul_f32 v[4:5], v[12:13], v[14:15]
	s_waitcnt vmcnt(2)
	v_lshlrev_b32_e32 v9, 16, v17
	v_mul_f32_e32 v4, v4, v5
	v_lshlrev_b32_e32 v5, 16, v16
	v_cvt_pk_bf16_f32 v7, v8, v4
	v_mul_f32_e32 v4, 0xbfb8aa3b, v5
	v_exp_f32_e32 v4, v4
	global_store_dwordx2 v[18:19], v[6:7], off offset:64
	v_and_b32_e32 v7, 0xffff0000, v16
	v_and_b32_e32 v11, 0xffff0000, v17
	v_add_f32_e32 v4, 1.0, v4
	v_rcp_f32_e32 v13, v4
	v_mul_f32_e32 v4, 0xbfb8aa3b, v7
	v_exp_f32_e32 v6, v4
	v_mov_b32_e32 v4, v0
	v_pk_mul_f32 v[4:5], v[12:13], v[4:5]
	v_add_f32_e32 v0, 1.0, v6
	v_rcp_f32_e32 v13, v0
	v_mul_f32_e32 v0, 0xbfb8aa3b, v9
	v_exp_f32_e32 v8, v0
	v_mul_f32_e32 v4, v4, v5
	v_mov_b32_e32 v6, v1
	v_pk_mul_f32 v[0:1], v[12:13], v[6:7]
	v_add_f32_e32 v5, 1.0, v8
	v_rcp_f32_e32 v13, v5
	v_mul_f32_e32 v5, 0xbfb8aa3b, v11
	v_exp_f32_e32 v5, v5
	v_mov_b32_e32 v8, v2
	v_mul_f32_e32 v6, v0, v1
	v_pk_mul_f32 v[0:1], v[12:13], v[8:9]
	v_add_f32_e32 v2, 1.0, v5
	v_rcp_f32_e32 v13, v2
	v_cvt_pk_bf16_f32 v2, v4, v6
	v_mul_f32_e32 v4, v0, v1
	v_pk_mul_f32 v[0:1], v[12:13], v[10:11]
	s_nop 0
	v_mul_f32_e32 v0, v0, v1
	v_cvt_pk_bf16_f32 v3, v4, v0
	global_store_dwordx2 v[18:19], v[2:3], off offset:96
